# attention unit prologues: queue atomic no longer waited at issue (returns into its register), kinf+Q+first-tile loads issued back to back in the diff mixer, wave0 log-forget load hoisted in the forget
# speedup vs baseline: 1.0119x; 1.0119x over previous
; __global__ void __launch_bounds__(512, 2) fwd_kernel(Args a) {
;     ...
;     for (int l = 0; l < DEPTH; ++l) {
;         const int pb = 1 + 6 * l;
;         const bf16* W1l = W1T + (size_t)l * NW1 * D;
;         if (EN(1) && IN(pb)) {
.LBB0_130:
	v_readlane_b32 s4, v255, 12
	s_add_i32 s4, s4, 1
	v_readlane_b32 s0, v254, 54
	v_readlane_b32 s1, v254, 55
	s_add_u32 s0, s0, 0x1000
	s_addc_u32 s1, s1, 0
	v_writelane_b32 v254, s0, 54
	v_readlane_b32 s5, v255, 13
	s_nop 0
	v_writelane_b32 v254, s1, 55
	s_nop 0
	v_readlane_b32 s0, v254, 56
	v_readlane_b32 s1, v254, 57
	s_add_u32 s0, s0, 0x2108000
	s_addc_u32 s1, s1, 0
	v_writelane_b32 v254, s0, 56
	s_cmp_eq_u32 s4, 4
	s_nop 0
	v_writelane_b32 v254, s1, 57
	s_cbranch_scc1 .LBB0_794
.LBB0_131:
	s_mul_i32 s0, s4, 6
	v_writelane_b32 v255, s0, 11
	s_or_b32 s2, s0, 1
	s_mov_b32 s6, s4
	s_mul_i32 s1, s4, 0x1100000
	v_readlane_b32 s3, v252, 40
	s_mul_hi_u32 s0, s4, 0x1100000
	v_writelane_b32 v255, s6, 12
	s_add_u32 s1, s3, s1
	s_addc_u32 s0, s55, s0
	v_writelane_b32 v255, s7, 13
	v_writelane_b32 v255, s1, 14
	s_cmp_le_i32 s90, s2
	v_writelane_b32 v255, s0, 15
	s_cselect_b64 s[0:1], -1, 0
	s_cmp_lt_i32 s2, s91
	s_cselect_b64 s[2:3], -1, 0
	s_and_b64 s[0:1], s[0:1], s[2:3]
	s_and_b64 vcc, exec, s[0:1]
	s_mov_b64 s[4:5], -1
	s_cbranch_vccnz .LBB0_133
	v_readlane_b32 s0, v255, 11
	s_add_i32 s0, s0, 2
	s_mov_b64 s[4:5], 0

.LBB0_239:
	v_mov_b32_e32 v206, 0
	s_and_saveexec_b64 s[4:5], s[34:35]
	s_cbranch_execz .LBB0_243
	s_mov_b64 s[8:9], exec
	v_mbcnt_lo_u32_b32 v0, s8, 0
	v_mbcnt_hi_u32_b32 v0, s9, v0
	v_cmp_eq_u32_e32 vcc, 0, v0
	s_and_saveexec_b64 s[6:7], vcc
	s_cbranch_execz .LBB0_242
	s_bcnt1_i32_b64 s2, s[8:9]
	v_mov_b32_e32 v2, s2
	global_atomic_add v206, v1, v2, s[48:49] sc0

; __device__ __forceinline__ float bflo(unsigned w) { return __uint_as_float(w << 16); }
; __device__ __forceinline__ float bfhi(unsigned w) { return __uint_as_float(w & 0xffff0000u); }
; __device__ __forceinline__ float xhalf_sum(float v) { auto rr = __builtin_amdgcn_permlane32_swap(__float_as_uint(v), __float_as_uint(v), false, false); return __uint_as_float(rr[0]) + __uint_as_float(rr[1]); }
; template <int MODE> ...
;     ...
;     { const bf16* qp = QK + (tok0 + wq0 + r32) * N1A + qcol + hi * 8;
; #pragma unroll
;       for (int d0 = 0; d0 < 4; ++d0) qr[d0] = *(const bf16x8*)(qp + d0 * 16); }
;     float qkb = 0.f;
;     if (REV) {
; #pragma unroll
;         for (int d0 = 0; d0 < 4; ++d0) { const u32x4 w = __builtin_bit_cast(u32x4, qr[d0]);
;             qkb += fabsf(pg8::bflo(w.x)) + fabsf(pg8::bfhi(w.x)) + fabsf(pg8::bflo(w.y)) + fabsf(pg8::bfhi(w.y)) + fabsf(pg8::bflo(w.z)) + fabsf(pg8::bfhi(w.z)) + fabsf(pg8::bflo(w.w)) + fabsf(pg8::bfhi(w.w)); }
;         qkb = xhalf_sum(qkb) * kinf * 1.02f;
;     }
;     const int t_lo = MODE == 1 ? (q0 >= 128 ? (q0 - 128) / 64 : 0) : 0, t_hi = (q0 + ROWS) / 64;
;     int kgoff[NKL], kloff[NKL], vgoff[NVL], vloff[NVL];
; #pragma unroll
;     for (int i = 0; i < NKL; ++i) { const int idx = tid + 512 * i, row = idx / KCH, ch = idx % KCH; kgoff[i] = row * N1A + ch * 8; kloff[i] = row * KSTR + ch * 16; }
; #pragma unroll
;     for (int i = 0; i < NVL; ++i) { const int idx = tid + 512 * i, row = idx >> 3, ch = idx & 7; vgoff[i] = row * M + ch * 8; vloff[i] = row * VSTR + ch * 16; }
;     u32x4 kstA[NKL], vstA[NVL], kstB[NKL], vstB[NVL]; float lfA = 0.f, lfB = 0.f, carry = 0.f;
; __device__ __forceinline__ void attn_phase(LAS unsigned char* lds, const Args& a, int layer, int vcu, int G) {
;     ...
;     ATT_QUEUE(0, 128, { const int s = 31 - (int)(u >> 2), h = 3 - (int)(u & 3u); const float sl2 = exp2f(-2.0f * (float)(h + 1)) * LOG2E;
;         int l15_ = threadIdx.x & 15; asm volatile("" : "+v"(l15_)); float kinf = kabs[(b * 16 + l15_) * 11 + 2 + (h >> 1)];
;         _Pragma("unroll") for (int o = 1; o < 16; o <<= 1) kinf = fmaxf(kinf, __shfl_xor(kinf, o));
;         attn_unit<0>(lds, QK, VT, Y, logf, b, h, s, sl2, 0.f, lam, subfac, subg, kinf); });
.LBB0_243:
	s_or_b64 exec, exec, s[4:5]
	v_mov_b32_e32 v2, v197
	s_lshl_b32 s2, s1, 1
	s_andn2_b32 s5, 3, s1
	s_or_b32 s2, s2, -8
	v_add_u32_e32 v2, s86, v2
	s_not_b32 s1, s1
	v_ldexp_f32 v0, 1.0, s2
	v_mul_lo_u32 v2, v2, 11
	s_bfe_u32 s2, s1, 0x10001
	v_add3_u32 v2, v2, s2, 2
	v_ashrrev_i32_e32 v3, 31, v2
	v_lshl_add_u64 v[2:3], v[2:3], 2, s[88:89]
	global_load_dword v150, v[2:3], off
	s_lshl_b32 s1, s1, 5
	s_and_b32 s70, s1, 0xf80
	s_lshl_b32 s8, s5, 8
	v_mul_f32_e32 v208, 0x3fb8aa3b, v0
	v_mov_b32_e32 v2, v196
	s_nop 0
	v_readfirstlane_b32 s76, v2
	s_ashr_i32 s2, s76, 6
	s_and_b32 s84, s2, 3
	s_lshl_b32 s1, s84, 5
	s_ashr_i32 s77, s76, 8
	s_or_b32 s71, s1, s70
	s_lshl_b32 s1, s5, 7
	s_lshl_b32 s4, s77, 6
	s_add_i32 s4, s4, s1
	s_add_u32 s10, s22, s8
	v_and_b32_e32 v178, 31, v2
	s_addc_u32 s11, s26, 0
	s_or_b32 s75, s71, s87
	v_or_b32_e32 v0, s75, v178
	v_mul_u32_u24_e32 v0, 0x1600, v0
	v_bfe_u32 v5, v2, 5, 1
	s_lshl_b32 s9, s5, 23
	v_lshl_add_u64 v[6:7], s[80:81], 0, v[0:1]
	s_ashr_i32 s5, s4, 31
	v_lshl_add_u64 v[6:7], s[4:5], 1, v[6:7]
	v_lshlrev_b32_e32 v0, 4, v5
	v_lshl_add_u64 v[6:7], v[6:7], 0, v[0:1]
	global_load_dwordx4 v[98:101], v[6:7], off
	global_load_dwordx4 v[102:105], v[6:7], off offset:32
	global_load_dwordx4 v[106:109], v[6:7], off offset:64
	global_load_dwordx4 v[110:113], v[6:7], off offset:96
	s_movk_i32 s4, 0x110
	s_add_u32 s12, s3, s9
	s_addc_u32 s13, s0, 0
	s_add_i32 s14, s70, 0x80
	s_lshr_b32 s20, s14, 6
	s_add_i32 s68, s20, -1
	v_and_b32_e32 v209, 63, v2
	v_add_u32_e32 v8, 0x200, v2
	v_ashrrev_i32_e32 v4, 31, v2
	v_lshrrev_b32_e32 v4, 28, v4
	v_add_u32_e32 v4, v2, v4
	v_ashrrev_i32_e32 v7, 4, v4
	v_and_b32_e32 v4, 0xffffff0, v4
	v_sub_u32_e32 v4, v2, v4
	v_mul_lo_u32 v6, v7, s4
	v_lshl_add_u32 v4, v4, 4, v6
	v_ashrrev_i32_e32 v6, 31, v8
	v_lshrrev_b32_e32 v6, 28, v6
	v_add_u32_e32 v6, v8, v6
	v_ashrrev_i32_e32 v14, 4, v6
	v_and_b32_e32 v6, 0xffffff0, v6
	v_lshlrev_b32_e32 v3, 4, v2
	v_sub_u32_e32 v6, v8, v6
	v_and_b32_e32 v16, 0x70, v3
	v_ashrrev_i32_e32 v3, 3, v2
	v_ashrrev_i32_e32 v8, 3, v8
	v_mul_lo_u32 v9, v14, s4
	v_mad_u64_u32 v[10:11], s[4:5], v3, s25, v[16:17]
	v_mad_u64_u32 v[12:13], s[4:5], v8, s25, v[16:17]
	s_mul_i32 s4, s68, 0x58000
	v_lshl_add_u32 v6, v6, 4, v9
	s_mul_hi_u32 s5, s68, 0x58000
	s_add_u32 s4, s10, s4
	v_lshl_or_b32 v2, v8, 16, v16
	s_addc_u32 s5, s11, s5
	s_lshl_b64 s[6:7], s[68:69], 7
	v_mad_u64_u32 v[8:9], s[36:37], v7, s21, v[4:5]
	v_mad_u64_u32 v[14:15], s[36:37], v14, s21, v[6:7]
	global_load_dwordx4 v[114:117], v8, s[4:5] offset:1024
	global_load_dwordx4 v[118:121], v14, s[4:5] offset:1024
	s_add_u32 s4, s12, s6
	s_addc_u32 s5, s13, s7
	v_lshl_or_b32 v16, v3, 16, v16
	global_load_dwordx4 v[122:125], v16, s[4:5]
	global_load_dwordx4 v[126:129], v2, s[4:5]
	s_waitcnt vmcnt(8)
	ds_bpermute_b32 v151, v179, v150
	v_max_f32_e32 v150, v150, v150
	s_waitcnt lgkmcnt(0)
	v_max_f32_e32 v151, v151, v151
	v_max_f32_e32 v150, v150, v151
	ds_bpermute_b32 v151, v192, v150
	s_waitcnt lgkmcnt(0)
	v_max_f32_e32 v151, v151, v151
	v_max_f32_e32 v150, v150, v151
	ds_bpermute_b32 v151, v193, v150
	s_waitcnt lgkmcnt(0)
	v_max_f32_e32 v151, v151, v151
	v_max_f32_e32 v150, v150, v151
	ds_bpermute_b32 v151, v194, v150
	s_waitcnt lgkmcnt(0)
	v_max_f32_e32 v151, v151, v151
	v_max_f32_e32 v151, v150, v151
	s_waitcnt vmcnt(7)
	v_lshlrev_b32_e32 v152, 16, v98
	s_waitcnt vmcnt(6)
; __device__ __forceinline__ float bflo(unsigned w) { return __uint_as_float(w << 16); }
; __device__ __forceinline__ float bfhi(unsigned w) { return __uint_as_float(w & 0xffff0000u); }
; __device__ __forceinline__ float xhalf_sum(float v) { auto rr = __builtin_amdgcn_permlane32_swap(__float_as_uint(v), __float_as_uint(v), false, false); return __uint_as_float(rr[0]) + __uint_as_float(rr[1]); }
; template <int MODE> ...
;     ...
;         for (int d0 = 0; d0 < 4; ++d0) { const u32x4 w = __builtin_bit_cast(u32x4, qr[d0]);
;             qkb += fabsf(pg8::bflo(w.x)) + fabsf(pg8::bfhi(w.x)) + fabsf(pg8::bflo(w.y)) + fabsf(pg8::bfhi(w.y)) + fabsf(pg8::bflo(w.z)) + fabsf(pg8::bfhi(w.z)) + fabsf(pg8::bflo(w.w)) + fabsf(pg8::bfhi(w.w)); }
;         qkb = xhalf_sum(qkb) * kinf * 1.02f;
;     }
;     const int t_lo = MODE == 1 ? (q0 >= 128 ? (q0 - 128) / 64 : 0) : 0, t_hi = (q0 + ROWS) / 64;
;     int kgoff[NKL], kloff[NKL], vgoff[NVL], vloff[NVL];
; #pragma unroll
;     for (int i = 0; i < NKL; ++i) { const int idx = tid + 512 * i, row = idx / KCH, ch = idx % KCH; kgoff[i] = row * N1A + ch * 8; kloff[i] = row * KSTR + ch * 16; }
; #pragma unroll
;     for (int i = 0; i < NVL; ++i) { const int idx = tid + 512 * i, row = idx >> 3, ch = idx & 7; vgoff[i] = row * M + ch * 8; vloff[i] = row * VSTR + ch * 16; }
;     u32x4 kstA[NKL], vstA[NVL], kstB[NKL], vstB[NVL]; float lfA = 0.f, lfB = 0.f, carry = 0.f;
	v_lshlrev_b32_e32 v154, 16, v102
	v_and_b32_e32 v155, 0x7fffffff, v154
	v_and_b32_e32 v154, 0x7fffffff, v152
	v_and_b32_e32 v152, 0xffff0000, v102
	v_and_b32_e32 v156, 0xffff0000, v98
	v_and_b32_e32 v157, 0x7fffffff, v152
	v_and_b32_e32 v156, 0x7fffffff, v156
	v_pk_add_f32 v[154:155], v[154:155], v[156:157]
	v_lshlrev_b32_e32 v152, 16, v99
	v_lshlrev_b32_e32 v156, 16, v103
	v_and_b32_e32 v157, 0x7fffffff, v156
	v_and_b32_e32 v156, 0x7fffffff, v152
	v_pk_add_f32 v[154:155], v[156:157], v[154:155]
	v_and_b32_e32 v152, 0xffff0000, v103
	v_and_b32_e32 v156, 0xffff0000, v99
	v_and_b32_e32 v157, 0x7fffffff, v152
	v_and_b32_e32 v156, 0x7fffffff, v156
	v_pk_add_f32 v[154:155], v[156:157], v[154:155]
	v_lshlrev_b32_e32 v152, 16, v100
	v_lshlrev_b32_e32 v156, 16, v104
	v_and_b32_e32 v157, 0x7fffffff, v156
	v_and_b32_e32 v156, 0x7fffffff, v152
	v_pk_add_f32 v[154:155], v[156:157], v[154:155]
	v_and_b32_e32 v152, 0xffff0000, v104
	v_and_b32_e32 v156, 0xffff0000, v100
	v_and_b32_e32 v157, 0x7fffffff, v152
	v_and_b32_e32 v156, 0x7fffffff, v156
	v_pk_add_f32 v[154:155], v[156:157], v[154:155]
	v_lshlrev_b32_e32 v152, 16, v101
	v_lshlrev_b32_e32 v156, 16, v105
	v_and_b32_e32 v157, 0x7fffffff, v156
	v_and_b32_e32 v156, 0x7fffffff, v152
	v_pk_add_f32 v[154:155], v[156:157], v[154:155]
	v_and_b32_e32 v152, 0xffff0000, v105
	v_and_b32_e32 v156, 0xffff0000, v101
	v_and_b32_e32 v157, 0x7fffffff, v152
	v_and_b32_e32 v156, 0x7fffffff, v156
	v_pk_add_f32 v[154:155], v[156:157], v[154:155]
	s_waitcnt vmcnt(5)
	v_lshlrev_b32_e32 v152, 16, v106
	s_waitcnt vmcnt(4)
	v_lshlrev_b32_e32 v156, 16, v110
	v_and_b32_e32 v157, 0x7fffffff, v156
	v_and_b32_e32 v156, 0x7fffffff, v152
	v_and_b32_e32 v152, 0xffff0000, v110
	v_and_b32_e32 v158, 0xffff0000, v106
	v_and_b32_e32 v159, 0x7fffffff, v152
	v_and_b32_e32 v158, 0x7fffffff, v158
	v_pk_add_f32 v[156:157], v[156:157], v[158:159]
	v_lshlrev_b32_e32 v152, 16, v107
	v_lshlrev_b32_e32 v158, 16, v111
	v_and_b32_e32 v159, 0x7fffffff, v158
	v_and_b32_e32 v158, 0x7fffffff, v152
	v_pk_add_f32 v[156:157], v[158:159], v[156:157]
	v_and_b32_e32 v152, 0xffff0000, v111
	v_and_b32_e32 v158, 0xffff0000, v107
	v_and_b32_e32 v159, 0x7fffffff, v152
	v_and_b32_e32 v158, 0x7fffffff, v158
	v_pk_add_f32 v[156:157], v[158:159], v[156:157]
	v_lshlrev_b32_e32 v152, 16, v108
	v_lshlrev_b32_e32 v158, 16, v112
	v_and_b32_e32 v159, 0x7fffffff, v158
	v_and_b32_e32 v158, 0x7fffffff, v152
	v_pk_add_f32 v[156:157], v[158:159], v[156:157]
	v_and_b32_e32 v152, 0xffff0000, v112
	v_and_b32_e32 v158, 0xffff0000, v108
	v_and_b32_e32 v159, 0x7fffffff, v152
	v_and_b32_e32 v158, 0x7fffffff, v158
	v_pk_add_f32 v[156:157], v[158:159], v[156:157]
	v_lshlrev_b32_e32 v152, 16, v109
	v_lshlrev_b32_e32 v158, 16, v113
	v_and_b32_e32 v159, 0x7fffffff, v158
	v_and_b32_e32 v158, 0x7fffffff, v152
	v_pk_add_f32 v[156:157], v[158:159], v[156:157]
	v_and_b32_e32 v152, 0xffff0000, v113
	v_and_b32_e32 v158, 0xffff0000, v109
	v_and_b32_e32 v159, 0x7fffffff, v152
	v_and_b32_e32 v158, 0x7fffffff, v158
	v_pk_add_f32 v[154:155], v[154:155], v[154:155] op_sel:[0,1] op_sel_hi:[1,0]
	v_pk_add_f32 v[156:157], v[158:159], v[156:157]
	s_nop 0
	v_pk_add_f32 v[154:155], v[154:155], v[156:157]
	s_nop 0
	v_pk_add_f32 v[154:155], v[154:155], v[156:157] op_sel:[0,1] op_sel_hi:[1,0]
	v_mov_b32_e32 v152, v154
	s_nop 1
	v_permlane32_swap_b32_e32 v154, v152
	v_add_f32_e32 v152, v154, v152
	v_mul_f32_e32 v151, v151, v152
	v_mul_f32_e32 v198, 0x3f828f5c, v151
	v_add_u32_e32 v212, 0, v10
	v_add_u32_e32 v214, 0, v12
	s_cmp_lt_u32 s76, 64
	v_cmp_le_f32_e32 vcc, s33, v198
	v_add_u32_e32 v210, 0, v4
	v_add_u32_e32 v211, 0, v6
	v_add_u32_e32 v213, 0x8800, v212
	v_add_u32_e32 v215, 0x8800, v214
	s_cselect_b64 s[4:5], -1, 0
	s_cmp_gt_u32 s76, 63
	s_waitcnt vmcnt(3)
	ds_write_b128 v210, v[114:117]
	s_waitcnt vmcnt(2)
	ds_write_b128 v211, v[118:121]
	s_waitcnt vmcnt(1)
	ds_write2_b64 v213, v[122:123], v[124:125] offset1:1
	s_waitcnt vmcnt(0)
	ds_write2_b64 v215, v[126:127], v[128:129] offset1:1
	s_cbranch_scc1 .LBB0_245
	s_lshl_b32 s6, s68, 6
	s_sub_i32 s6, s6, s70
	v_or_b32_e32 v3, s6, v209
	v_cvt_f32_i32_e32 v3, v3
	v_lshl_add_u32 v4, v209, 2, 0
	v_add_u32_e32 v4, 0x11000, v4
	v_mul_f32_e32 v3, v208, v3
	ds_write_b32 v4, v3

.LBB0_320:
	v_mov_b32_e32 v131, 0
	s_and_saveexec_b64 s[6:7], s[34:35]
	s_cbranch_execz .LBB0_324
	s_mov_b64 s[10:11], exec
	v_mbcnt_lo_u32_b32 v0, s10, 0
	v_mbcnt_hi_u32_b32 v0, s11, v0
	v_cmp_eq_u32_e32 vcc, 0, v0
	s_and_saveexec_b64 s[8:9], vcc
	s_cbranch_execz .LBB0_323
	s_bcnt1_i32_b64 s2, s[10:11]
	v_mov_b32_e32 v2, s2
	global_atomic_add v131, v1, v2, s[4:5] offset:2048 sc0

; __device__ __forceinline__ float bflo(unsigned w) { return __uint_as_float(w << 16); }
; __device__ __forceinline__ float bfhi(unsigned w) { return __uint_as_float(w & 0xffff0000u); }
; __device__ __forceinline__ float xhalf_sum(float v) { auto rr = __builtin_amdgcn_permlane32_swap(__float_as_uint(v), __float_as_uint(v), false, false); return __uint_as_float(rr[0]) + __uint_as_float(rr[1]); }
; template <int MODE> ...
;     ...
;     { const bf16* qp = QK + (tok0 + wq0 + r32) * N1A + qcol + hi * 8;
; #pragma unroll
;       for (int d0 = 0; d0 < 4; ++d0) qr[d0] = *(const bf16x8*)(qp + d0 * 16); }
;     float qkb = 0.f;
;     if (REV) {
; #pragma unroll
;         for (int d0 = 0; d0 < 4; ++d0) { const u32x4 w = __builtin_bit_cast(u32x4, qr[d0]);
;             qkb += fabsf(pg8::bflo(w.x)) + fabsf(pg8::bfhi(w.x)) + fabsf(pg8::bflo(w.y)) + fabsf(pg8::bfhi(w.y)) + fabsf(pg8::bflo(w.z)) + fabsf(pg8::bfhi(w.z)) + fabsf(pg8::bflo(w.w)) + fabsf(pg8::bfhi(w.w)); }
;         qkb = xhalf_sum(qkb) * kinf * 1.02f;
;     }
;     const int t_lo = MODE == 1 ? (q0 >= 128 ? (q0 - 128) / 64 : 0) : 0, t_hi = (q0 + ROWS) / 64;
;     int kgoff[NKL], kloff[NKL], vgoff[NVL], vloff[NVL];
; #pragma unroll
;     for (int i = 0; i < NKL; ++i) { const int idx = tid + 512 * i, row = idx / KCH, ch = idx % KCH; kgoff[i] = row * N1A + ch * 8; kloff[i] = row * KSTR + ch * 16; }
; #pragma unroll
;     for (int i = 0; i < NVL; ++i) { const int idx = tid + 512 * i, row = idx >> 3, ch = idx & 7; vgoff[i] = row * M + ch * 8; vloff[i] = row * VSTR + ch * 16; }
;     u32x4 kstA[NKL], vstA[NVL], kstB[NKL], vstB[NVL]; float lfA = 0.f, lfB = 0.f, carry = 0.f;
; __device__ __forceinline__ void attn_phase(LAS unsigned char* lds, const Args& a, int layer, int vcu, int G) {
;     ...
;     ATT_QUEUE(1, 128, { const int s = 15 - (int)(u >> 3), h = (int)(u & 7u);
;         int l15_ = threadIdx.x & 15; asm volatile("" : "+v"(l15_)); float kinf = kabs[(b * 16 + l15_) * 11 + 8 + (h >> 2)];
;         _Pragma("unroll") for (int o = 1; o < 16; o <<= 1) kinf = fmaxf(kinf, __shfl_xor(kinf, o));
;         attn_unit<2>(lds, QK, VT, Y, logf, b, h, s, 0.f, 0.f, 0.f, 0.f, subg, kinf); });
.LBB0_324:
	s_or_b64 exec, exec, s[6:7]
	v_mov_b32_e32 v0, v197
	s_bfe_u32 s2, s13, 0x10002
	v_add_u32_e32 v0, s26, v0
	v_mul_lo_u32 v0, v0, 11
	v_add3_u32 v2, v0, s2, 8
	v_ashrrev_i32_e32 v3, 31, v2
	v_lshl_add_u64 v[2:3], v[2:3], 2, s[88:89]
	global_load_dword v10, v[2:3], off
	v_mov_b32_e32 v8, v196
	s_not_b32 s6, s13
	v_readfirstlane_b32 s2, v8
	s_ashr_i32 s15, s2, 6
	s_lshl_b32 s6, s6, 5
	s_and_b32 s12, s13, 7
	s_and_b32 s13, s6, 0xf00
	s_lshl_b32 s16, s15, 5
	s_add_i32 s84, s16, s13
	s_lshl_b32 s10, s12, 7
	s_add_u32 s8, s71, s10
	s_addc_u32 s9, s75, 0
	s_lshl_b32 s14, s12, 22
	s_add_u32 s18, s82, s14
	s_addc_u32 s19, s83, 0
	s_ashr_i32 s6, s84, 31
	v_and_b32_e32 v132, 31, v8
	s_add_u32 s77, s84, s70
	v_or_b32_e32 v0, s77, v132
	v_mov_b64_e32 v[2:3], s[80:81]
	s_addc_u32 s76, s6, 0
	v_mad_u64_u32 v[2:3], s[6:7], v0, s30, v[2:3]
	v_mov_b32_e32 v0, 0x1600
	v_bfe_u32 v7, v8, 5, 1
	s_mov_b32 s11, s69
	v_mad_i32_i24 v3, s76, v0, v3
	v_lshl_add_u64 v[4:5], v[2:3], 0, s[10:11]
	v_lshlrev_b32_e32 v2, 4, v7
	v_mov_b32_e32 v3, v1
	v_lshl_add_u64 v[4:5], v[4:5], 0, v[2:3]
	global_load_dwordx4 v[66:69], v[4:5], off offset:3072
	global_load_dwordx4 v[70:73], v[4:5], off offset:3104
	global_load_dwordx4 v[74:77], v[4:5], off offset:3136
	global_load_dwordx4 v[78:81], v[4:5], off offset:3168
	v_ashrrev_i32_e32 v0, 31, v8
	v_lshrrev_b32_e32 v0, 29, v0
	v_add_u32_e32 v11, v8, v0
	v_ashrrev_i32_e32 v12, 3, v11
	v_and_b32_e32 v4, 0xffffff8, v11
	s_movk_i32 s6, 0x90
	v_sub_u32_e32 v4, v8, v4
	v_mul_lo_u32 v5, v12, s6
	v_and_b32_e32 v3, 63, v8
	v_ashrrev_i32_e32 v9, 3, v8
	v_lshlrev_b32_e32 v6, 4, v8
	v_lshl_add_u32 v8, v4, 4, v5
	v_mad_u64_u32 v[4:5], s[6:7], v12, s73, v[8:9]
	s_add_u32 s11, s8, 0x1000
	s_addc_u32 s17, s9, 0
	s_add_i32 s6, s13, 0x100
	s_lshl_b32 s7, s70, 1
	s_add_u32 s7, s18, s7
	s_addc_u32 s8, s19, 0
	s_add_u32 s18, s7, 0x2000000
	s_addc_u32 s19, s8, 0
	s_lshr_b32 s85, s6, 6
	s_add_i32 s68, s85, -1
	s_mul_i32 s6, s68, 0x58000
	s_mul_hi_u32 s7, s68, 0x58000
	s_add_u32 s6, s11, s6
	s_addc_u32 s7, s17, s7
	s_lshl_b64 s[8:9], s[68:69], 7
	v_and_b32_e32 v6, 0x70, v6
	s_add_u32 s8, s18, s8
	v_lshl_or_b32 v0, v9, 16, v6
	s_addc_u32 s9, s19, s9
	global_load_dwordx4 v[82:85], v4, s[6:7]
	global_load_dwordx4 v[86:89], v0, s[8:9]
	s_waitcnt vmcnt(39)
	v_mov_b32_e32 v133, 0
	s_cmp_gt_u32 s2, 63
	s_cbranch_scc1 .Lfox_nolf
	s_lshl_b32 s98, s68, 6
	s_add_i32 s98, s98, s70
	v_or_b32_e32 v90, s98, v3
	v_mov_b32_e32 v91, v1
	v_readlane_b32 s100, v253, 62
	v_lshlrev_b64 v[90:91], 5, v[90:91]
	v_readlane_b32 s101, v253, 63
	s_lshl_b32 s98, s12, 2
	s_mov_b32 s99, 0
	v_lshl_add_u64 v[90:91], s[100:101], 0, v[90:91]
	v_lshl_add_u64 v[90:91], v[90:91], 0, s[98:99]
	global_load_dword v133, v[90:91], off
.Lfox_nolf:
	s_cmp_lt_u32 s2, 64
	s_cselect_b64 s[8:9], -1, 0
	s_cmp_gt_u32 s2, 63
	s_cselect_b64 s[6:7], -1, 0
	v_mov_b32_e32 v137, 0
	s_and_b64 vcc, exec, s[6:7]
	s_waitcnt vmcnt(6)
	ds_bpermute_b32 v5, v179, v10
	v_max_f32_e32 v10, v10, v10
	s_waitcnt lgkmcnt(0)
	v_max_f32_e32 v5, v5, v5
	v_max_f32_e32 v5, v10, v5
	ds_bpermute_b32 v10, v192, v5
	s_waitcnt lgkmcnt(0)
	v_max_f32_e32 v10, v10, v10
	v_max_f32_e32 v5, v5, v10
	ds_bpermute_b32 v20, v193, v5
	s_waitcnt lgkmcnt(0)
	v_max_f32_e32 v20, v20, v20
	v_max_f32_e32 v5, v5, v20
	ds_bpermute_b32 v20, v194, v5
	s_waitcnt vmcnt(5)
	v_lshlrev_b32_e32 v10, 16, v66
	s_waitcnt vmcnt(4)
	v_lshlrev_b32_e32 v11, 16, v70
	v_and_b32_e32 v12, 0xffff0000, v70
	v_and_b32_e32 v14, 0xffff0000, v66
	v_lshlrev_b32_e32 v16, 16, v67
	v_lshlrev_b32_e32 v15, 16, v71
	v_and_b32_e32 v11, 0x7fffffff, v11
	v_and_b32_e32 v10, 0x7fffffff, v10
	v_and_b32_e32 v13, 0x7fffffff, v12
	v_and_b32_e32 v12, 0x7fffffff, v14
	v_and_b32_e32 v17, 0xffff0000, v71
	v_and_b32_e32 v18, 0xffff0000, v67
	v_and_b32_e32 v15, 0x7fffffff, v15
	v_and_b32_e32 v14, 0x7fffffff, v16
	v_pk_add_f32 v[10:11], v[10:11], v[12:13]
	v_lshlrev_b32_e32 v21, 16, v68
	v_lshlrev_b32_e32 v19, 16, v72
	v_and_b32_e32 v17, 0x7fffffff, v17
	v_and_b32_e32 v16, 0x7fffffff, v18
	v_pk_add_f32 v[10:11], v[14:15], v[10:11]
	s_waitcnt lgkmcnt(0)
	v_max_f32_e32 v12, v20, v20
	v_and_b32_e32 v19, 0x7fffffff, v19
	v_and_b32_e32 v18, 0x7fffffff, v21
	v_pk_add_f32 v[10:11], v[16:17], v[10:11]
	v_max_f32_e32 v5, v5, v12
	v_and_b32_e32 v12, 0xffff0000, v72
	v_and_b32_e32 v14, 0xffff0000, v68
	v_pk_add_f32 v[10:11], v[18:19], v[10:11]
	v_and_b32_e32 v13, 0x7fffffff, v12
	v_and_b32_e32 v12, 0x7fffffff, v14
	v_pk_add_f32 v[10:11], v[12:13], v[10:11]
	v_lshlrev_b32_e32 v12, 16, v69
	v_lshlrev_b32_e32 v13, 16, v73
	v_and_b32_e32 v13, 0x7fffffff, v13
	v_and_b32_e32 v12, 0x7fffffff, v12
	v_pk_add_f32 v[10:11], v[12:13], v[10:11]
	v_and_b32_e32 v12, 0xffff0000, v73
	v_and_b32_e32 v14, 0xffff0000, v69
	v_and_b32_e32 v13, 0x7fffffff, v12
	v_and_b32_e32 v12, 0x7fffffff, v14
	v_pk_add_f32 v[10:11], v[12:13], v[10:11]
	s_waitcnt vmcnt(3)
	v_lshlrev_b32_e32 v12, 16, v74
	s_waitcnt vmcnt(2)
	v_lshlrev_b32_e32 v13, 16, v78
	v_and_b32_e32 v14, 0xffff0000, v78
	v_and_b32_e32 v16, 0xffff0000, v74
	v_and_b32_e32 v13, 0x7fffffff, v13
	v_and_b32_e32 v12, 0x7fffffff, v12
	v_and_b32_e32 v15, 0x7fffffff, v14
	v_and_b32_e32 v14, 0x7fffffff, v16
	v_pk_add_f32 v[12:13], v[12:13], v[14:15]
	v_lshlrev_b32_e32 v14, 16, v75
	v_lshlrev_b32_e32 v15, 16, v79
	v_and_b32_e32 v15, 0x7fffffff, v15
	v_and_b32_e32 v14, 0x7fffffff, v14
	v_pk_add_f32 v[12:13], v[14:15], v[12:13]
	v_and_b32_e32 v14, 0xffff0000, v79
	v_and_b32_e32 v16, 0xffff0000, v75
	v_and_b32_e32 v15, 0x7fffffff, v14
	v_and_b32_e32 v14, 0x7fffffff, v16
	v_pk_add_f32 v[12:13], v[14:15], v[12:13]
	v_lshlrev_b32_e32 v14, 16, v76
	v_lshlrev_b32_e32 v15, 16, v80
	v_and_b32_e32 v15, 0x7fffffff, v15
	v_and_b32_e32 v14, 0x7fffffff, v14
	v_pk_add_f32 v[12:13], v[14:15], v[12:13]
	v_and_b32_e32 v14, 0xffff0000, v80
	v_and_b32_e32 v16, 0xffff0000, v76
	v_and_b32_e32 v15, 0x7fffffff, v14
	v_and_b32_e32 v14, 0x7fffffff, v16
	v_pk_add_f32 v[12:13], v[14:15], v[12:13]
	v_lshlrev_b32_e32 v14, 16, v77
	v_lshlrev_b32_e32 v15, 16, v81
	v_and_b32_e32 v15, 0x7fffffff, v15
	v_and_b32_e32 v14, 0x7fffffff, v14
	v_pk_add_f32 v[12:13], v[14:15], v[12:13]
	v_and_b32_e32 v14, 0xffff0000, v81
	v_and_b32_e32 v16, 0xffff0000, v77
	v_and_b32_e32 v15, 0x7fffffff, v14
	v_and_b32_e32 v14, 0x7fffffff, v16
	v_pk_add_f32 v[10:11], v[10:11], v[10:11] op_sel:[0,1] op_sel_hi:[1,0]
	v_pk_add_f32 v[12:13], v[14:15], v[12:13]
	s_nop 0
	v_pk_add_f32 v[10:11], v[10:11], v[12:13]
	s_nop 0
	v_pk_add_f32 v[10:11], v[10:11], v[12:13] op_sel:[0,1] op_sel_hi:[1,0]
	s_nop 0
	v_mov_b32_e32 v11, v10
	s_nop 1
	v_permlane32_swap_b32_e32 v10, v11
	v_add_f32_e32 v10, v10, v11
	v_mul_f32_e32 v5, v5, v10
	v_mul_f32_e32 v198, 0x3f828f5c, v5
	v_cmp_le_f32_e64 s[38:39], s33, v198

; template <int MODE> ...
;     ...
;     const int tid = tid_, lane = tid & 63, wid = __builtin_amdgcn_readfirstlane(tid >> 6), r32 = lane & 31, hi = lane >> 5;
;     const int q0 = qblk * ROWS, wq0 = q0 + 32 * (MODE == 2 ? wid : MODE == 1 ? (wid & 1) : (wid & 3)), mapi = MODE == 2 ? 0 : MODE == 1 ? (wid >> 1) : (wid >> 2), heff = MODE == 1 ? h + mapi : h;
;     const float sl2w = MODE == 1 ? sl2 * (1.0f / (float)(1 << mapi)) : sl2, sink2w = MODE == 1 ? subg[heff] * LOG2E : sink2;
;     const size_t tok0 = (size_t)b * SEQ;
;     const int qcol = MODE == 0 ? h * 128 + mapi * 64 : MODE == 1 ? 1024 + heff * 64 : 1536 + h * 64;
;     const int kcol = MODE == 0 ? 512 + h * 128 : MODE == 1 ? 2560 + (h >> 2) * 64 : 2048 + h * 64;
;     const int vrow = MODE == 0 ? h * 128 : MODE == 1 ? 1024 + (h >> 2) * 64 : 512 + h * 64;
;     const int ycol = MODE == 0 ? h * 128 : MODE == 1 ? 512 + heff * 64 : 1024 + h * 64;
;     const bf16* Kg = QK + tok0 * N1A + kcol;
;     const bf16* Vg = VT + (size_t)vrow * M + tok0;
;     bf16x8 qr[4];
;     { const bf16* qp = QK + (tok0 + wq0 + r32) * N1A + qcol + hi * 8;
; #pragma unroll
;       for (int d0 = 0; d0 < 4; ++d0) qr[d0] = *(const bf16x8*)(qp + d0 * 16); }
;     float qkb = 0.f;
;     if (REV) {
; #pragma unroll
;         for (int d0 = 0; d0 < 4; ++d0) { const u32x4 w = __builtin_bit_cast(u32x4, qr[d0]);
;             qkb += fabsf(pg8::bflo(w.x)) + fabsf(pg8::bfhi(w.x)) + fabsf(pg8::bflo(w.y)) + fabsf(pg8::bfhi(w.y)) + fabsf(pg8::bflo(w.z)) + fabsf(pg8::bfhi(w.z)) + fabsf(pg8::bflo(w.w)) + fabsf(pg8::bfhi(w.w)); }
;         qkb = xhalf_sum(qkb) * kinf * 1.02f;
;     }
;     const int t_lo = MODE == 1 ? (q0 >= 128 ? (q0 - 128) / 64 : 0) : 0, t_hi = (q0 + ROWS) / 64;
;     int kgoff[NKL], kloff[NKL], vgoff[NVL], vloff[NVL];
; #pragma unroll
;     for (int i = 0; i < NKL; ++i) { const int idx = tid + 512 * i, row = idx / KCH, ch = idx % KCH; kgoff[i] = row * N1A + ch * 8; kloff[i] = row * KSTR + ch * 16; }
; #pragma unroll
;     for (int i = 0; i < NVL; ++i) { const int idx = tid + 512 * i, row = idx >> 3, ch = idx & 7; vgoff[i] = row * M + ch * 8; vloff[i] = row * VSTR + ch * 16; }
;     u32x4 kstA[NKL], vstA[NVL], kstB[NKL], vstB[NVL]; float lfA = 0.f, lfB = 0.f, carry = 0.f;
;     ...
;     float mrun = NEG, lsum = 0.f;
;     if (MODE == 1) { mrun = sink2w + sl2w * (float)(wq0 + r32 - q0); lsum = hi == 0 ? 1.f : 0.f; }
.LBB0_399:
	v_mov_b32_e32 v118, 0
	s_and_saveexec_b64 s[4:5], s[34:35]
	s_cbranch_execz .LBB0_403
	s_mov_b64 s[8:9], exec
	v_mbcnt_lo_u32_b32 v0, s8, 0
	v_mbcnt_hi_u32_b32 v0, s9, v0
	v_cmp_eq_u32_e32 vcc, 0, v0
	s_and_saveexec_b64 s[6:7], vcc
	s_cbranch_execz .LBB0_402
	s_bcnt1_i32_b64 s2, s[8:9]
	v_mov_b32_e32 v2, s2
	global_atomic_add v118, v1, v2, s[42:43] sc0
.LBB0_402:
	s_or_b64 exec, exec, s[6:7]
.LBB0_403:
	s_or_b64 exec, exec, s[4:5]
	s_lshl_b32 s2, s20, 2
	s_and_b32 s6, s2, 4
	s_or_b32 s2, s6, 1
	v_cvt_f32_ubyte0_e32 v0, s2
	s_mov_b32 s2, 0x42fc0000
	v_cmp_lt_f32_e32 vcc, s2, v0
	v_mov_b32_e32 v2, 0x42800000
	s_lshr_b32 s17, s20, 1
	v_cndmask_b32_e32 v2, 0, v2, vcc
	v_sub_f32_e32 v0, v2, v0
	v_exp_f32_e32 v0, v0
	v_mov_b32_e32 v9, v196
	s_and_b64 s[4:5], vcc, exec
	s_cselect_b32 s2, 0xffffffc0, 0
	v_readfirstlane_b32 s11, v9
	s_ashr_i32 s22, s11, 7
	v_ldexp_f32 v0, v0, s2
	s_lshl_b32 s5, 1, s22
	v_mul_f32_e32 v8, 0x3fb8aa3b, v0
	v_cvt_f32_i32_e32 v0, s5
	s_add_i32 s4, s22, s6
	s_ashr_i32 s19, s11, 6
	s_and_b32 s18, s19, 1
	v_div_scale_f32 v2, s[6:7], v0, v0, 1.0
	v_rcp_f32_e32 v3, v2
	s_lshl_b32 s2, s17, 6
	s_lshl_b32 s10, s18, 5
	s_ashr_i32 s5, s4, 31
	s_or_b32 s16, s10, s2
	v_fma_f32 v4, -v2, v3, 1.0
	s_lshl_b64 s[6:7], s[4:5], 2
	v_fmac_f32_e32 v3, v4, v3
	v_div_scale_f32 v4, vcc, 1.0, v0, 1.0
	s_add_u32 s6, s0, s6
	v_mul_f32_e32 v5, v4, v3
	s_addc_u32 s7, s1, s7
	s_lshl_b32 s5, s20, 6
	v_fma_f32 v7, -v2, v5, v4
	s_and_b32 s5, s5, 64
	v_fmac_f32_e32 v5, v7, v3
	global_load_dword v7, v1, s[6:7]
	s_lshl_b32 s4, s4, 6
	s_lshl_b32 s6, s5, 1
	s_add_u32 s8, s13, s6
	s_addc_u32 s9, s14, 0
	s_lshl_b32 s5, s5, 16
	v_fma_f32 v2, -v2, v5, v4
	s_add_u32 s6, s82, s5
	v_and_b32_e32 v119, 31, v9
	v_div_fmas_f32 v2, v2, v3, v5
	s_addc_u32 s7, s83, 0
	s_or_b32 s15, s16, s12
	v_div_fixup_f32 v10, v2, v0, 1.0
	v_or_b32_e32 v0, s15, v119
	s_ashr_i32 s5, s4, 31
	s_lshl_b32 s23, s12, 1
	v_mul_lo_u32 v0, v0, s30
	s_add_u32 s6, s6, s23
	v_lshl_add_u64 v[2:3], s[80:81], 0, v[0:1]
	s_addc_u32 s7, s7, 0
	v_ashrrev_i32_e32 v0, 31, v9
	v_bfe_u32 v120, v9, 5, 1
	s_add_u32 s6, s6, 0x4000000
	v_lshrrev_b32_e32 v0, 29, v0
	v_lshl_add_u64 v[4:5], s[4:5], 1, v[2:3]
	v_lshlrev_b32_e32 v2, 4, v120
	v_mov_b32_e32 v3, v1
	s_addc_u32 s7, s7, 0
	s_add_i32 s23, s2, 0xffffff80
	v_add_u32_e32 v0, v9, v0
	v_lshl_add_u64 v[4:5], v[4:5], 0, v[2:3]
	s_lshr_b32 s23, s23, 6
	v_ashrrev_i32_e32 v3, 3, v0
	v_and_b32_e32 v0, 0xffffff8, v0
	global_load_dwordx4 v[66:69], v[4:5], off offset:2048
	global_load_dwordx4 v[70:73], v[4:5], off offset:2080
	global_load_dwordx4 v[74:77], v[4:5], off offset:2112
	global_load_dwordx4 v[78:81], v[4:5], off offset:2144
	s_cmp_gt_u32 s20, 3
	v_sub_u32_e32 v5, v9, v0
	v_lshlrev_b32_e32 v0, 4, v9
	v_mul_f32_e32 v121, v8, v10
	s_cselect_b32 s44, s23, 0
	v_ashrrev_i32_e32 v10, 3, v9
	v_and_b32_e32 v4, 0x70, v0
	s_add_u32 s8, s8, 0x1400
	v_lshl_or_b32 v0, v10, 16, v4
	s_addc_u32 s9, s9, 0
	s_movk_i32 s20, 0x90
	v_mad_u64_u32 v[10:11], s[36:37], v10, s25, v[4:5]
	s_mul_i32 s23, s44, 0x58000
	v_mul_lo_u32 v8, v3, s20
	s_mov_b32 s45, s69
	s_mul_hi_u32 s20, s44, 0x58000
	s_add_u32 s36, s8, s23
	v_lshl_add_u32 v8, v5, 4, v8
	s_addc_u32 s37, s9, s20
	s_lshl_b64 s[38:39], s[44:45], 7
	s_add_u32 s38, s6, s38
	v_mad_u64_u32 v[4:5], s[40:41], v3, s73, v[8:9]
	s_addc_u32 s39, s7, s39
	global_load_dwordx4 v[82:85], v4, s[36:37]
	global_load_dwordx4 v[86:89], v0, s[38:39]
	s_cmp_eq_u32 s18, 0
	s_cselect_b64 s[46:47], -1, 0
	s_cmp_eq_u32 s18, 1
	v_add_u32_e32 v124, 0, v10
	s_cselect_b64 s[36:37], -1, 0
	v_and_b32_e32 v6, 63, v9
	v_add_u32_e32 v123, 0, v8
	v_add_u32_e32 v125, 0x8800, v124
	s_and_b64 vcc, exec, s[36:37]
	s_waitcnt vmcnt(1)
	ds_write_b128 v123, v[82:85]
	s_waitcnt vmcnt(0)
	ds_write2_b64 v125, v[86:87], v[88:89] offset1:1
	s_cbranch_vccnz .LBB0_405
	s_sub_i32 s18, s44, s17
	v_lshl_or_b32 v3, s18, 6, v6
	v_cvt_f32_i32_e32 v3, v3
	s_and_b32 s18, s11, 0x3fffff80
	s_lshl_b32 s18, s18, 2
	s_add_i32 s18, s18, 0
	v_lshl_add_u32 v5, v6, 2, s18
	v_mul_f32_e32 v3, v121, v3
	v_add_u32_e32 v5, 0x11800, v5
	ds_write_b32 v5, v3

; #define SEAM(k) do { if (IN(k) && IN((k) + 1)) { if ((k) == 0) { cg::this_grid().sync(); bar = xcd_barrier_post((unsigned*)(a.ws + WS_BAR), bst); } else xcd_barrier(bar); } } while (0)
; __global__ void __launch_bounds__(512, 2) fwd_kernel(Args a) {
;     ...
;         if (EN(2) && IN(pb + 1)) attn_phase(lds, a, l, vcu, G);
;         SEAM(pb + 1);
;         if (EN(3) && IN(pb + 2)) { pg8::Gemm g{XB, W1l + (size_t)(N1A + N1V) * D, M, N1B, D}; pg8::StaticOrder S; S.init(M, N1B, G, bx); pg8::EpiG1b E{Yb, GM};
.LBB0_493:
	s_or_b64 exec, exec, s[4:5]
	s_waitcnt lgkmcnt(0)
	s_barrier
.LBB0_494:
	s_cmp_le_i32 s90, s0
	s_cselect_b64 s[2:3], -1, 0
	s_cmp_lt_i32 s0, s91
	s_cselect_b64 s[0:1], -1, 0
	s_and_b64 s[0:1], s[2:3], s[0:1]
	s_mov_b64 s[4:5], -1
	s_and_b64 vcc, exec, s[0:1]
	s_cbranch_vccnz .LBB0_496
	v_readlane_b32 s0, v255, 11
	s_add_i32 s0, s0, 4
	s_mov_b64 s[4:5], 0

; #define SEAM(k) do { if (IN(k) && IN((k) + 1)) { if ((k) == 0) { cg::this_grid().sync(); bar = xcd_barrier_post((unsigned*)(a.ws + WS_BAR), bst); } else xcd_barrier(bar); } } while (0)
; __global__ void __launch_bounds__(512, 2) fwd_kernel(Args a) {
;     ...
;             pg8::gemm_phase<pg8::EpiG1b, pg8::StaticOrder, true, true>(lds, g, S, E); }
;         SEAM(pb + 2);
;         if (EN(4) && IN(pb + 3)) { pg8::Gemm g{Yb, WUPT + (size_t)l * D * 1536, M, D, 1536}; pg8::StaticOrder S; S.init(M, D, G, bx); pg8::EpiG3a E{GM, XB};
.LBB0_566:
	s_or_b64 exec, exec, s[4:5]
	s_waitcnt lgkmcnt(0)
	s_barrier
.LBB0_567:
	s_cmp_le_i32 s90, s0
	s_cselect_b64 s[2:3], -1, 0
	s_cmp_lt_i32 s0, s91
	s_cselect_b64 s[0:1], -1, 0
	s_and_b64 s[0:1], s[2:3], s[0:1]
	s_mov_b64 s[4:5], -1
	s_and_b64 vcc, exec, s[0:1]
	s_cbranch_vccnz .LBB0_569
	v_readlane_b32 s0, v255, 11
	s_add_i32 s0, s0, 5
	s_mov_b64 s[4:5], 0
